# attention: fused prefix chain Q+=Q*e (no separate 1+e adds), cross-half exchange by v_permlane32_swap instead of ds_bpermute
# baseline (speedup 1.0000x reference)
; #define LAS __attribute__((address_space(3)))
; __device__ __forceinline__ unsigned pk2(float lo, float hi) { return pg8::cvt_pk_bf16(lo, hi); }
; #define AT_PV(W, off) do { const bf16x8 pf_ = __builtin_bit_cast(bf16x8, W); \
;                 const bf16x8 v0_ = *(const LAS bf16x8*)(vb + (off)), v1_ = *(const LAS bf16x8*)(vb + 4608 + (off)); \
;                 o0 = __builtin_amdgcn_mfma_f32_32x32x16_bf16(v0_, pf_, o0, 0, 0, 0); o1 = __builtin_amdgcn_mfma_f32_32x32x16_bf16(v1_, pf_, o1, 0, 0, 0); } while (0)
;     ...
; #pragma unroll
;             for (int r = 14; r >= 0; --r) { p0[r] *= p0[r + 1]; p1[r] *= p1[r + 1]; }
;             const float L0 = p0[0], L1 = p1[0];
;             const float pL0 = __shfl_xor(L0, 32), pL1 = __shfl_xor(L1, 32);
;             const float tot1 = L1 * pL1;
;             const float pre1 = hi ? C : C * pL1;
;             const float pre0 = C * tot1 * (hi ? 1.f : pL0);
;             C = C * tot1 * (L0 * pL0);
; #pragma unroll
;             for (int r = 0; r < 15; ++r) { p0[r] = pre0 * (p0[r + 1] - p0[r]); p1[r] = pre1 * (p1[r + 1] - p1[r]); }
;             p0[15] = pre0 * (1.f - p0[15]); p1[15] = pre1 * (1.f - p1[15]);
;             u32x4 w00, w01, w10, w11;
;             w00.x = pk2(p0[0], p0[1]); w00.y = pk2(p0[2], p0[3]); w00.z = pk2(p0[4], p0[5]); w00.w = pk2(p0[6], p0[7]);
;             w01.x = pk2(p0[8], p0[9]); w01.y = pk2(p0[10], p0[11]); w01.z = pk2(p0[12], p0[13]); w01.w = pk2(p0[14], p0[15]);
;             w10.x = pk2(p1[0], p1[1]); w10.y = pk2(p1[2], p1[3]); w10.z = pk2(p1[4], p1[5]); w10.w = pk2(p1[6], p1[7]);
;             w11.x = pk2(p1[8], p1[9]); w11.y = pk2(p1[10], p1[11]); w11.z = pk2(p1[12], p1[13]); w11.w = pk2(p1[14], p1[15]);
;             const LAS unsigned char* vb = lds + AT_V + cur * 9216 + r32 * 144 + hi * 32;
;     ...
;             AT_PV(w00, 0); AT_PV(w01, 16); AT_PV(w10, 64); AT_PV(w11, 80);
;     ...
;             alive = __any(C != 0.f);
.Lattn_nomask:
	v_add_f32_e32 v156, 1.0, v32
	v_add_f32_e32 v168, 1.0, v40
	v_add_f32_e32 v176, 1.0, v48
	v_add_f32_e32 v184, 1.0, v56
	v_mul_f32_e32 v33, v156, v33
	v_mul_f32_e32 v41, v168, v41
	v_mul_f32_e32 v49, v176, v49
	v_mul_f32_e32 v57, v184, v57
	v_add_f32_e32 v157, v156, v33
	v_add_f32_e32 v169, v168, v41
	v_add_f32_e32 v177, v176, v49
	v_add_f32_e32 v185, v184, v57
	v_mul_f32_e32 v34, v157, v34
	v_mul_f32_e32 v42, v169, v42
	v_mul_f32_e32 v50, v177, v50
	v_mul_f32_e32 v58, v185, v58
	v_add_f32_e32 v158, v157, v34
	v_add_f32_e32 v170, v169, v42
	v_add_f32_e32 v178, v177, v50
	v_add_f32_e32 v186, v185, v58
	v_mul_f32_e32 v35, v158, v35
	v_mul_f32_e32 v43, v170, v43
	v_mul_f32_e32 v51, v178, v51
	v_mul_f32_e32 v59, v186, v59
	v_add_f32_e32 v159, v158, v35
	v_add_f32_e32 v171, v170, v43
	v_add_f32_e32 v179, v178, v51
	v_add_f32_e32 v187, v186, v59
	v_mul_f32_e32 v36, v159, v36
	v_mul_f32_e32 v44, v171, v44
	v_mul_f32_e32 v52, v179, v52
	v_mul_f32_e32 v60, v187, v60
	v_add_f32_e32 v160, v159, v36
	v_add_f32_e32 v172, v171, v44
	v_add_f32_e32 v180, v179, v52
	v_add_f32_e32 v188, v187, v60
	v_mul_f32_e32 v37, v160, v37
	v_mul_f32_e32 v45, v172, v45
	v_mul_f32_e32 v53, v180, v53
	v_mul_f32_e32 v61, v188, v61
	v_add_f32_e32 v161, v160, v37
	v_add_f32_e32 v173, v172, v45
	v_add_f32_e32 v181, v180, v53
	v_add_f32_e32 v189, v188, v61
	v_mul_f32_e32 v38, v161, v38
	v_mul_f32_e32 v46, v173, v46
	v_mul_f32_e32 v54, v181, v54
	v_mul_f32_e32 v62, v189, v62
	v_add_f32_e32 v162, v161, v38
	v_add_f32_e32 v174, v173, v46
	v_add_f32_e32 v182, v181, v54
	v_add_f32_e32 v190, v189, v62
	v_mul_f32_e32 v39, v162, v39
	v_mul_f32_e32 v47, v174, v47
	v_mul_f32_e32 v55, v182, v55
	v_mul_f32_e32 v63, v190, v63
	v_add_f32_e32 v163, v162, v39
	v_add_f32_e32 v175, v174, v47
	v_add_f32_e32 v183, v182, v55
	v_add_f32_e32 v191, v190, v63
	v_rcp_f32_e32 v246, v163
	v_rcp_f32_e32 v247, v175
	v_rcp_f32_e32 v248, v183
	v_rcp_f32_e32 v249, v191
	s_nop 0
	v_mul_f32_e32 v250, v246, v247
	v_mul_f32_e32 v251, v248, v249
	v_mul_f32_e32 v230, v246, v247
	v_mul_f32_e32 v231, v248, v249
	s_nop 1
	v_permlane32_swap_b32_e32 v250, v230
	v_permlane32_swap_b32_e32 v251, v231
	s_nop 1
	v_mul_f32_e32 v237, v251, v231
	v_mul_f32_e32 v238, v95, v231
	v_cndmask_b32_e64 v239, 1.0, v230, s[36:37]
	v_mul_f32_e32 v237, v95, v237
	v_cndmask_b32_e64 v238, v95, v238, s[36:37]
	v_mul_f32_e32 v230, v250, v230
	v_mul_f32_e32 v239, v237, v239
	v_mul_f32_e32 v95, v237, v230
	v_mul_f32_e32 v239, v239, v247
	v_mul_f32_e32 v238, v238, v249
	v_cmp_neq_f32_e32 vcc, 0, v95
	v_mul_f32_e32 v237, v239, v246
	v_mul_f32_e32 v231, v238, v248
	s_cmp_lg_u64 vcc, 0
	s_cselect_b64 s[4:5], -1, 0
	v_mul_f32_e32 v32, v237, v32
	v_mul_f32_e32 v33, v237, v33
	v_mul_f32_e32 v34, v237, v34
	v_mul_f32_e32 v35, v237, v35
	v_mul_f32_e32 v36, v237, v36
	v_mul_f32_e32 v37, v237, v37
	v_mul_f32_e32 v38, v237, v38
	v_mul_f32_e32 v39, v237, v39
	v_mul_f32_e32 v40, v239, v40
	v_mul_f32_e32 v41, v239, v41
	v_mul_f32_e32 v42, v239, v42
	v_mul_f32_e32 v43, v239, v43
	v_mul_f32_e32 v44, v239, v44
	v_mul_f32_e32 v45, v239, v45
	v_mul_f32_e32 v46, v239, v46
	v_mul_f32_e32 v47, v239, v47
	v_mul_f32_e32 v48, v231, v48
	v_mul_f32_e32 v49, v231, v49
	v_mul_f32_e32 v50, v231, v50
	v_mul_f32_e32 v51, v231, v51
	v_mul_f32_e32 v52, v231, v52
	v_mul_f32_e32 v53, v231, v53
	v_mul_f32_e32 v54, v231, v54
	v_mul_f32_e32 v55, v231, v55
	v_mul_f32_e32 v56, v238, v56
	v_mul_f32_e32 v57, v238, v57
	v_mul_f32_e32 v58, v238, v58
	v_mul_f32_e32 v59, v238, v59
	v_mul_f32_e32 v60, v238, v60
	v_mul_f32_e32 v61, v238, v61
	v_mul_f32_e32 v62, v238, v62
	v_mul_f32_e32 v63, v238, v63
	v_cvt_pk_bf16_f32 v142, v32, v33
	v_cvt_pk_bf16_f32 v143, v34, v35
	v_cvt_pk_bf16_f32 v144, v36, v37
	v_cvt_pk_bf16_f32 v145, v38, v39
	v_cvt_pk_bf16_f32 v146, v40, v41
	v_cvt_pk_bf16_f32 v147, v42, v43
	v_cvt_pk_bf16_f32 v148, v44, v45
	v_cvt_pk_bf16_f32 v149, v46, v47
	v_cvt_pk_bf16_f32 v150, v48, v49
	v_cvt_pk_bf16_f32 v151, v50, v51
	v_cvt_pk_bf16_f32 v152, v52, v53
	v_cvt_pk_bf16_f32 v153, v54, v55
	v_cvt_pk_bf16_f32 v242, v56, v57
	v_cvt_pk_bf16_f32 v243, v58, v59
	v_cvt_pk_bf16_f32 v244, v60, v61
	v_cvt_pk_bf16_f32 v245, v62, v63
	s_waitcnt lgkmcnt(0)
	v_mfma_f32_32x32x16_bf16 v[16:31], v[206:209], v[142:145], v[16:31]
	v_mfma_f32_32x32x16_bf16 v[0:15], v[210:213], v[142:145], v[0:15]
	v_mfma_f32_32x32x16_bf16 v[16:31], v[214:217], v[146:149], v[16:31]
	v_mfma_f32_32x32x16_bf16 v[0:15], v[218:221], v[146:149], v[0:15]
	v_mfma_f32_32x32x16_bf16 v[16:31], v[222:225], v[150:153], v[16:31]
	v_mfma_f32_32x32x16_bf16 v[0:15], v[226:229], v[150:153], v[0:15]
	v_mfma_f32_32x32x16_bf16 v[16:31], v[118:121], v[242:245], v[16:31]
	v_mfma_f32_32x32x16_bf16 v[0:15], v[122:125], v[242:245], v[0:15]
	v_cndmask_b32_e64 v32, 0, 1, s[4:5]
	s_andn2_b64 vcc, exec, s[12:13]
	s_cbranch_vccz .LBB0_472
